# NSA item prologue: K/V-tile reuse barrier moved from before the compressed K/V loads and QK-norm math to right before the first LDS tile write
# baseline (speedup 1.0000x reference)
; DI void nsa_item(unsigned char* ws_, const float* qg, const bf16_t* proj, bf16_t* mix, int item, LP unsigned char* lds3) {
;     ...
;   const int tid = TIDX(), lane = tid & 63, wave = tid >> 6, r = lane & 31, hh = lane >> 5;
;   const int qt = 31 - (item >> 6), bg = item & 63, b = bg >> 2, g = bg & 3;
;   const int hd = wave & 3, th = wave >> 2, tl = th * 32 + r, t = qt * 64 + tl;
;   bf16_t* Ks = (bf16_t*)lds;
;   bf16_t* VTs = (bf16_t*)(lds + 18432);
;   float* imp = (float*)(lds + 35840);
;   unsigned* msk = (unsigned*)(lds + 68608);
;   float* cmb = (float*)(lds + 69632) + tid;
;   const size_t tokrow = (size_t)(b * 2048 + t) * LDP0;
;   bf16x8 qf[4];
;   {
;     float qv[4][8]; float ss = 0.f;
; #pragma unroll
;     for (int kk = 0; kk < 4; ++kk) { unpack8(*(const u32x4*)(proj + tokrow + N_Q + (g * 4 + hd) * 64 + kk * 16 + 8 * hh), qv[kk]);
; #pragma unroll
;       for (int e = 0; e < 8; ++e) ss += qv[kk][e] * qv[kk][e]; }
;     ss += __shfl_xor(ss, 32);
;     const float rstd = rsqrtf(ss * (1.f / 64.f) + EPS) * 0.18033688011112042f;
; #pragma unroll
;     for (int kk = 0; kk < 4; ++kk) { const f32x4 g0v = *(const f32x4*)(qg + kk * 16 + 8 * hh), g1v = *(const f32x4*)(qg + kk * 16 + 8 * hh + 4);
;       qf[kk] = pack8(qv[kk][0] * rstd * g0v[0], qv[kk][1] * rstd * g0v[1], qv[kk][2] * rstd * g0v[2], qv[kk][3] * rstd * g0v[3],
;                      qv[kk][4] * rstd * g1v[0], qv[kk][5] * rstd * g1v[1], qv[kk][6] * rstd * g1v[2], qv[kk][7] * rstd * g1v[3]); } }
;   const float g0 = sigmf(bf2f(proj[tokrow + N_GT + (g * 4 + hd) * 3 + 0]));
;   const float g1 = sigmf(bf2f(proj[tokrow + N_GT + (g * 4 + hd) * 3 + 1]));
;   const float g2 = sigmf(bf2f(proj[tokrow + N_GT + (g * 4 + hd) * 3 + 2]));
;   __syncthreads();
;   { const bf16_t* kc = (const bf16_t*)(p.ws + WS_KCMP) + (size_t)bg * 128 * 64; const bf16_t* vc = (const bf16_t*)(p.ws + WS_VCMP) + (size_t)bg * 64 * 128;
; #pragma unroll
;     for (int i = 0; i < 2; ++i) { const int idx = tid + 512 * i; { const int n = idx >> 3, c = idx & 7; *(u32x4*)(Ks + n * 72 + c * 8) = *(const u32x4*)(kc + n * 64 + c * 8); }
;       { const int dd = idx >> 4, c = idx & 15; *(u32x4*)(VTs + dd * 136 + c * 8) = *(const u32x4*)(vc + dd * 128 + c * 8); } } }
; __global__ void __launch_bounds__(512, 2) fwd_mega(Params p_unused) {
;     ...
;         __syncthreads();
;         if (TIDX() == 0) s_item = (int)atomicAdd(qctr, 1u);
.LBB0_395:
	s_or_b64 exec, exec, s[2:3]
	s_mov_b64 s[2:3], src_shared_base
	v_mov_b32_e32 v171, s3
	s_waitcnt lgkmcnt(0)
	s_barrier
	flat_load_dword v3, v[170:171] sc0 sc1
	s_waitcnt vmcnt(0)
	s_movk_i32 s2, 0x880
	s_waitcnt lgkmcnt(0)
	v_cmp_gt_i32_e32 vcc, s2, v3
	s_mov_b64 s[2:3], -1
	s_mov_b64 s[4:5], exec
	v_writelane_b32 v252, s4, 52
	s_nop 1
	v_writelane_b32 v252, s5, 53
	s_and_b64 s[4:5], s[4:5], vcc
	s_mov_b64 exec, s[4:5]
	s_cbranch_execz .LBB0_390
	s_movk_i32 s2, 0x7f
	v_cmp_lt_i32_e32 vcc, s2, v3
	s_and_saveexec_b64 s[2:3], vcc
	s_xor_b64 s[2:3], exec, s[2:3]
	v_writelane_b32 v252, s2, 54
	s_nop 1
	v_writelane_b32 v252, s3, 55
	s_cbranch_execz .LBB0_645
	v_readlane_b32 s2, v252, 38
	v_add_u32_e32 v86, 0xffffff80, v3
	v_readlane_b32 s3, v252, 39
	v_mov_b32_e32 v84, v185
	v_lshrrev_b32_e32 v108, 6, v86
	s_load_dwordx2 s[2:3], s[2:3], 0x78
	v_xor_b32_e32 v100, 31, v108
	v_ashrrev_i32_e32 v106, 3, v84
	s_movk_i32 s4, 0xffe0
	v_bfi_b32 v109, s4, v106, v84
	v_lshlrev_b32_e32 v110, 6, v100
	v_readlane_b32 s4, v252, 40
	v_bfe_u32 v85, v3, 2, 4
	v_add_u32_e32 v101, v109, v110
	v_readlane_b32 s5, v252, 41
	v_and_b32_e32 v107, 3, v3
	v_lshl_add_u32 v88, v85, 11, v101
	v_mov_b64_e32 v[0:1], s[4:5]
	v_bfe_u32 v91, v84, 6, 2
	v_mad_i64_i32 v[64:65], s[4:5], v88, s97, v[0:1]
	v_lshlrev_b32_e32 v0, 9, v107
	v_bfe_u32 v89, v84, 5, 1
	v_lshl_or_b32 v168, v91, 7, v0
	v_lshl_add_u64 v[0:1], v[64:65], 0, v[168:169]
	v_lshlrev_b32_e32 v32, 4, v89
	v_mov_b32_e32 v33, v169
	v_lshl_add_u64 v[0:1], v[0:1], 0, v[32:33]
	s_mov_b64 s[4:5], 0x1820
	v_lshl_add_u64 v[4:5], v[0:1], 0, s[4:5]
	s_movk_i32 s4, 0x1000
	v_add_co_u32_e32 v0, vcc, s4, v0
	global_load_dwordx4 v[42:45], v[4:5], off offset:96
	global_load_dwordx4 v[50:53], v[4:5], off offset:64
	global_load_dwordx4 v[58:61], v[4:5], off offset:32
	v_addc_co_u32_e32 v1, vcc, 0, v1, vcc
	global_load_dwordx4 v[70:73], v[0:1], off offset:2080
	v_and_b32_e32 v1, 64, v199
	v_xor_b32_e32 v0, 32, v199
	v_add_u32_e32 v1, 64, v1
	v_lshl_or_b32 v98, v107, 2, v91
	v_cmp_lt_i32_e32 vcc, v0, v1
	v_lshlrev_b32_e32 v20, 5, v89
	v_and_b32_e32 v33, 63, v3
	v_cndmask_b32_e32 v0, v199, v0, vcc
	v_lshlrev_b32_e32 v102, 2, v0
	s_waitcnt lgkmcnt(0)
	global_load_dwordx4 v[12:15], v20, s[2:3] offset:16
	global_load_dwordx4 v[28:31], v20, s[2:3]
	global_load_dwordx4 v[4:7], v20, s[2:3] offset:80
	global_load_dwordx4 v[8:11], v20, s[2:3] offset:64
	global_load_dwordx4 v[24:27], v20, s[2:3] offset:144
	global_load_dwordx4 v[0:3], v20, s[2:3] offset:128
	global_load_dwordx4 v[16:19], v20, s[2:3] offset:208
	s_nop 0
	global_load_dwordx4 v[20:23], v20, s[2:3] offset:192
	s_mov_b64 s[2:3], 0x2c20
	v_add_u32_e32 v103, 0x200, v84
	v_mov_b32_e32 v133, v169
	v_ashrrev_i32_e32 v111, 3, v103
	v_lshlrev_b32_e32 v78, 6, v111
	v_ashrrev_i32_e32 v79, 31, v78
	s_movk_i32 s4, 0x90
	s_movk_i32 s5, 0x110
	v_cmp_eq_u32_e64 s[6:7], 0, v89
	s_mov_b32 s90, 0xefa18f08
	s_waitcnt vmcnt(11)
	v_lshlrev_b32_e32 v34, 16, v45
	v_and_b32_e32 v35, 0xffff0000, v45
	v_lshlrev_b32_e32 v36, 16, v44
	v_and_b32_e32 v37, 0xffff0000, v44
	v_lshlrev_b32_e32 v38, 16, v43
	s_waitcnt vmcnt(8)
	v_lshlrev_b32_e32 v130, 16, v70
	v_and_b32_e32 v131, 0xffff0000, v70
	v_lshlrev_b32_e32 v62, 16, v71
	v_and_b32_e32 v63, 0xffff0000, v71
	v_pk_mul_f32 v[70:71], v[130:131], v[130:131]
	v_and_b32_e32 v39, 0xffff0000, v43
	v_lshlrev_b32_e32 v40, 16, v42
	v_and_b32_e32 v41, 0xffff0000, v42
	v_lshlrev_b32_e32 v42, 16, v53
	v_and_b32_e32 v43, 0xffff0000, v53
	v_lshlrev_b32_e32 v44, 16, v52
	v_and_b32_e32 v45, 0xffff0000, v52
	v_lshlrev_b32_e32 v46, 16, v51
	v_and_b32_e32 v47, 0xffff0000, v51
	v_lshlrev_b32_e32 v48, 16, v50
	v_and_b32_e32 v49, 0xffff0000, v50
	v_lshlrev_b32_e32 v50, 16, v61
	v_and_b32_e32 v51, 0xffff0000, v61
	v_lshlrev_b32_e32 v52, 16, v60
	v_and_b32_e32 v53, 0xffff0000, v60
	v_lshlrev_b32_e32 v54, 16, v59
	v_and_b32_e32 v55, 0xffff0000, v59
	v_lshlrev_b32_e32 v56, 16, v58
	v_and_b32_e32 v57, 0xffff0000, v58
	v_lshlrev_b32_e32 v58, 16, v73
	v_and_b32_e32 v59, 0xffff0000, v73
	v_lshlrev_b32_e32 v60, 16, v72
	v_and_b32_e32 v61, 0xffff0000, v72
	v_pk_mul_f32 v[72:73], v[62:63], v[62:63]
	v_add_f32_e32 v70, v70, v71
	v_add_f32_e32 v70, v72, v70
	v_pk_mul_f32 v[128:129], v[60:61], v[60:61]
	v_add_f32_e32 v70, v73, v70
	v_add_f32_e32 v90, v128, v70
	v_mul_u32_u24_e32 v70, 3, v98
	v_lshlrev_b32_e32 v168, 1, v70
	v_lshl_add_u64 v[64:65], v[64:65], 0, v[168:169]
	v_lshl_add_u64 v[70:71], v[64:65], 0, s[2:3]
	s_movk_i32 s2, 0x2000
	v_add_co_u32_e32 v64, vcc, s2, v64
	v_readlane_b32 s2, v252, 44
	s_nop 0
	v_addc_co_u32_e32 v65, vcc, 0, v65, vcc
	v_lshlrev_b32_e32 v168, 14, v33
	v_readlane_b32 s3, v252, 45
	global_load_dword v87, v[64:65], off offset:3104
	global_load_ushort v99, v[70:71], off offset:4
	v_lshl_add_u64 v[64:65], s[2:3], 0, v[168:169]
	v_readlane_b32 s2, v252, 48
	v_lshlrev_b32_e32 v33, 3, v84
	v_readlane_b32 s3, v252, 49
	v_and_b32_e32 v33, 56, v33
	v_ashrrev_i32_e32 v128, 4, v103
	v_lshl_add_u64 v[70:71], s[2:3], 0, v[168:169]
	v_lshlrev_b32_e32 v168, 1, v33
	v_lshlrev_b32_e32 v33, 4, v84
	v_and_b32_e32 v132, 0xf0, v33
	v_ashrrev_i32_e32 v33, 4, v84
	v_lshl_add_u64 v[112:113], v[70:71], 0, v[132:133]
	v_lshlrev_b32_e32 v70, 6, v106
	v_lshlrev_b32_e32 v72, 7, v33
	v_lshl_add_u64 v[64:65], v[64:65], 0, v[168:169]
	v_ashrrev_i32_e32 v71, 31, v70
	v_ashrrev_i32_e32 v73, 31, v72
	v_lshl_add_u64 v[70:71], v[70:71], 1, v[64:65]
	v_lshl_add_u64 v[74:75], v[72:73], 1, v[112:113]
	v_lshl_add_u64 v[64:65], v[78:79], 1, v[64:65]
	global_load_dwordx4 v[70:73], v[70:71], off
	s_nop 0
	global_load_dwordx4 v[74:77], v[74:75], off
	v_pk_mul_f32 v[126:127], v[58:59], v[58:59]
; DI float bf2f(bf16_t b) { return __uint_as_float(((unsigned)b) << 16); }
; DI float sigmf(float x) { return 1.f / (1.f + __expf(-x)); }
; #define MFMA32(a, b, c) __builtin_amdgcn_mfma_f32_32x32x16_bf16((a), (b), (c), 0, 0, 0)
; DI void nsa_item(unsigned char* ws_, const float* qg, const bf16_t* proj, bf16_t* mix, int item, LP unsigned char* lds3) {
;     ...
;   {
;     float qv[4][8]; float ss = 0.f;
; #pragma unroll
;     for (int kk = 0; kk < 4; ++kk) { unpack8(*(const u32x4*)(proj + tokrow + N_Q + (g * 4 + hd) * 64 + kk * 16 + 8 * hh), qv[kk]);
; #pragma unroll
;       for (int e = 0; e < 8; ++e) ss += qv[kk][e] * qv[kk][e]; }
;     ss += __shfl_xor(ss, 32);
;     const float rstd = rsqrtf(ss * (1.f / 64.f) + EPS) * 0.18033688011112042f;
; #pragma unroll
;     for (int kk = 0; kk < 4; ++kk) { const f32x4 g0v = *(const f32x4*)(qg + kk * 16 + 8 * hh), g1v = *(const f32x4*)(qg + kk * 16 + 8 * hh + 4);
;       qf[kk] = pack8(qv[kk][0] * rstd * g0v[0], qv[kk][1] * rstd * g0v[1], qv[kk][2] * rstd * g0v[2], qv[kk][3] * rstd * g0v[3],
;                      qv[kk][4] * rstd * g1v[0], qv[kk][5] * rstd * g1v[1], qv[kk][6] * rstd * g1v[2], qv[kk][7] * rstd * g1v[3]); } }
;   const float g0 = sigmf(bf2f(proj[tokrow + N_GT + (g * 4 + hd) * 3 + 0]));
;   const float g1 = sigmf(bf2f(proj[tokrow + N_GT + (g * 4 + hd) * 3 + 1]));
;   const float g2 = sigmf(bf2f(proj[tokrow + N_GT + (g * 4 + hd) * 3 + 2]));
;   __syncthreads();
;   { const bf16_t* kc = (const bf16_t*)(p.ws + WS_KCMP) + (size_t)bg * 128 * 64; const bf16_t* vc = (const bf16_t*)(p.ws + WS_VCMP) + (size_t)bg * 64 * 128;
; #pragma unroll
;     for (int i = 0; i < 2; ++i) { const int idx = tid + 512 * i; { const int n = idx >> 3, c = idx & 7; *(u32x4*)(Ks + n * 72 + c * 8) = *(const u32x4*)(kc + n * 64 + c * 8); }
;       { const int dd = idx >> 4, c = idx & 15; *(u32x4*)(VTs + dd * 136 + c * 8) = *(const u32x4*)(vc + dd * 128 + c * 8); } } }
;   __syncthreads();
;   {
;     f32x16 x[4]; float mx = NEGF;
; #pragma unroll
;     for (int sub = 0; sub < 4; ++sub) { x[sub] = zero16();
; #pragma unroll
;       for (int kk = 0; kk < 4; ++kk) x[sub] = MFMA32(*(const bf16x8*)(Ks + (sub * 32 + r) * 72 + kk * 16 + 8 * hh), qf[kk], x[sub]);
	global_load_dwordx4 v[78:81], v[64:65], off
	v_lshlrev_b32_e32 v64, 7, v128
	v_ashrrev_i32_e32 v65, 31, v64
	v_lshl_add_u64 v[64:65], v[64:65], 1, v[112:113]
	global_load_dwordx4 v[112:115], v[64:65], off
	v_add_f32_e32 v64, v129, v90
	v_add_f32_e32 v64, v126, v64
	v_pk_mul_f32 v[124:125], v[56:57], v[56:57]
	v_add_f32_e32 v64, v127, v64
	v_add_f32_e32 v64, v124, v64
	v_pk_mul_f32 v[122:123], v[54:55], v[54:55]
	v_add_f32_e32 v64, v125, v64
	v_add_f32_e32 v64, v122, v64
	v_pk_mul_f32 v[120:121], v[52:53], v[52:53]
	v_add_f32_e32 v64, v123, v64
	v_add_f32_e32 v64, v120, v64
	v_pk_mul_f32 v[118:119], v[50:51], v[50:51]
	v_add_f32_e32 v64, v121, v64
	v_add_f32_e32 v64, v118, v64
	v_pk_mul_f32 v[116:117], v[48:49], v[48:49]
	v_add_f32_e32 v64, v119, v64
	v_add_f32_e32 v64, v116, v64
	v_pk_mul_f32 v[104:105], v[46:47], v[46:47]
	v_add_f32_e32 v64, v117, v64
	v_add_f32_e32 v64, v104, v64
	v_pk_mul_f32 v[96:97], v[44:45], v[44:45]
	v_add_f32_e32 v64, v105, v64
	v_add_f32_e32 v64, v96, v64
	v_pk_mul_f32 v[94:95], v[42:43], v[42:43]
	v_add_f32_e32 v64, v97, v64
	v_add_f32_e32 v64, v94, v64
	v_pk_mul_f32 v[92:93], v[40:41], v[40:41]
	v_add_f32_e32 v64, v95, v64
	v_add_f32_e32 v64, v92, v64
	v_pk_mul_f32 v[82:83], v[38:39], v[38:39]
	v_add_f32_e32 v64, v93, v64
	v_add_f32_e32 v64, v82, v64
	v_pk_mul_f32 v[68:69], v[36:37], v[36:37]
	v_add_f32_e32 v64, v83, v64
	v_add_f32_e32 v64, v68, v64
	v_pk_mul_f32 v[66:67], v[34:35], v[34:35]
	v_add_f32_e32 v64, v69, v64
	v_add_f32_e32 v64, v66, v64
	v_add_f32_e32 v64, v67, v64
	ds_bpermute_b32 v65, v102, v64
	v_mul_lo_u32 v94, v106, s4
	v_and_b32_e32 v90, 31, v84
	s_waitcnt lgkmcnt(0)
	v_add_f32_e32 v64, v64, v65
	v_fmamk_f32 v64, v64, 0x3c800000, v198
	v_mul_f32_e32 v65, 0x4b800000, v64
	v_cmp_gt_f32_e32 vcc, s92, v64
	s_waitcnt vmcnt(5)
	v_lshlrev_b32_e32 v93, 16, v87
	v_cndmask_b32_e32 v64, v64, v65, vcc
	v_rsq_f32_e32 v64, v64
	s_nop 0
	v_mul_f32_e32 v65, 0x45800000, v64
	v_cndmask_b32_e32 v64, v64, v65, vcc
	v_mul_f32_e32 v82, 0x3e38aa3b, v64
	v_pk_mul_f32 v[60:61], v[82:83], v[60:61] op_sel_hi:[0,1]
	v_pk_mul_f32 v[12:13], v[12:13], v[60:61]
	v_pk_mul_f32 v[58:59], v[82:83], v[58:59] op_sel_hi:[0,1]
	v_cvt_pk_bf16_f32 v66, v12, v13
	v_pk_mul_f32 v[12:13], v[82:83], v[56:57] op_sel_hi:[0,1]
	v_pk_mul_f32 v[8:9], v[8:9], v[12:13]
	v_pk_mul_f32 v[12:13], v[82:83], v[54:55] op_sel_hi:[0,1]
	v_pk_mul_f32 v[10:11], v[10:11], v[12:13]
	v_pk_mul_f32 v[12:13], v[82:83], v[52:53] op_sel_hi:[0,1]
	v_pk_mul_f32 v[14:15], v[14:15], v[58:59]
	v_pk_mul_f32 v[12:13], v[4:5], v[12:13]
	v_pk_mul_f32 v[4:5], v[82:83], v[50:51] op_sel_hi:[0,1]
	v_cvt_pk_bf16_f32 v67, v14, v15
	v_pk_mul_f32 v[14:15], v[6:7], v[4:5]
	v_add_u32_e32 v4, 32, v168
	v_add_u32_e32 v6, 32, v132
	v_cvt_pk_bf16_f32 v68, v8, v9
	v_add_u32_e32 v103, v4, v94
	v_mad_u64_u32 v[8:9], s[2:3], v33, s5, v[6:7]
	v_mad_u64_u32 v[4:5], s[2:3], v111, s4, v[4:5]
	v_add_u32_e32 v111, 32, v32
	s_waitcnt vmcnt(3)
	s_barrier
	ds_write_b128 v103, v[70:73]
	s_waitcnt vmcnt(2)
	ds_write_b128 v8, v[74:77] offset:18432
	s_waitcnt vmcnt(1)
	ds_write_b128 v4, v[78:81]
	v_mad_u64_u32 v[4:5], s[2:3], v128, s5, v[6:7]
	v_mad_u32_u24 v92, v90, s4, v111
	s_waitcnt vmcnt(0)
	ds_write_b128 v4, v[112:115] offset:18432
	s_waitcnt lgkmcnt(0)
	s_barrier
	ds_read_b128 v[4:7], v92
	v_pk_mul_f32 v[64:65], v[82:83], v[130:131] op_sel_hi:[0,1]
	v_pk_mul_f32 v[62:63], v[82:83], v[62:63] op_sel_hi:[0,1]
	v_pk_mul_f32 v[28:29], v[28:29], v[64:65]
	v_pk_mul_f32 v[30:31], v[30:31], v[62:63]
	v_pk_mul_f32 v[8:9], v[82:83], v[48:49] op_sel_hi:[0,1]
	v_cvt_pk_bf16_f32 v64, v28, v29
	v_cvt_pk_bf16_f32 v65, v30, v31
	v_pk_mul_f32 v[32:33], v[0:1], v[8:9]
	v_pk_mul_f32 v[0:1], v[82:83], v[46:47] op_sel_hi:[0,1]
	ds_read_b128 v[28:31], v92 offset:32
	v_cvt_pk_bf16_f32 v69, v10, v11
	v_cvt_pk_bf16_f32 v70, v12, v13
	v_cvt_pk_bf16_f32 v71, v14, v15
	v_pk_mul_f32 v[46:47], v[2:3], v[0:1]
	s_waitcnt lgkmcnt(1)
	v_mfma_f32_32x32x16_bf16 v[0:15], v[4:7], v[64:67], 0
	v_mul_f32_e64 v44, v82, v44
	v_mul_f32_e64 v45, v82, v45
	v_mul_f32_e64 v24, v24, v44
	v_mul_f32_e64 v25, v25, v45
	v_mul_f32_e64 v42, v82, v42
	v_mul_f32_e64 v43, v82, v43
	v_pk_mul_f32 v[42:43], v[26:27], v[42:43]
	v_cvt_pk_bf16_f32 v74, v24, v25
	ds_read_b128 v[24:27], v92 offset:64
	v_cvt_pk_bf16_f32 v72, v32, v33
	s_waitcnt lgkmcnt(1)
	v_mfma_f32_32x32x16_bf16 v[0:15], v[28:31], v[68:71], v[0:15]
	v_mul_f32_e64 v28, v82, v40
	v_mul_f32_e64 v29, v82, v41
	v_mul_f32_e64 v28, v20, v28
	v_mul_f32_e64 v29, v21, v29
	v_mul_f32_e64 v20, v82, v38
	v_mul_f32_e64 v21, v82, v39
	v_cvt_pk_bf16_f32 v73, v46, v47
	v_cvt_pk_bf16_f32 v75, v42, v43
	v_pk_mul_f32 v[30:31], v[22:23], v[20:21]
	ds_read_b128 v[20:23], v92 offset:96
	s_waitcnt lgkmcnt(1)
	v_mfma_f32_32x32x16_bf16 v[0:15], v[24:27], v[72:75], v[0:15]
	v_mul_f32_e64 v32, v82, v36
	v_mul_f32_e64 v33, v82, v37
	v_mul_f32_e64 v24, v82, v34
	v_mul_f32_e64 v25, v82, v35
	v_mul_f32_e64 v16, v16, v32
	v_mul_f32_e64 v17, v17, v33
	v_pk_mul_f32 v[18:19], v[18:19], v[24:25]
	v_cvt_pk_bf16_f32 v78, v16, v17
	v_cvt_pk_bf16_f32 v79, v18, v19
	ds_read_b128 v[16:19], v92 offset:4608
	ds_read_b128 v[32:35], v92 offset:4640
	v_cvt_pk_bf16_f32 v76, v28, v29
	v_cvt_pk_bf16_f32 v77, v30, v31
	s_waitcnt lgkmcnt(2)
	s_nop 0
	v_mfma_f32_32x32x16_bf16 v[0:15], v[20:23], v[76:79], v[0:15]
	s_waitcnt lgkmcnt(1)
	v_mfma_f32_32x32x16_bf16 v[16:31], v[16:19], v[64:67], 0
	s_waitcnt lgkmcnt(0)
	v_mfma_f32_32x32x16_bf16 v[16:31], v[32:35], v[68:71], v[16:31]
	ds_read_b128 v[32:35], v92 offset:4672
	ds_read_b128 v[36:39], v92 offset:4704
	s_waitcnt lgkmcnt(1)
; DI float bf2f(bf16_t b) { return __uint_as_float(((unsigned)b) << 16); }
; DI float sigmf(float x) { return 1.f / (1.f + __expf(-x)); }
; DI int crow(int reg, int h) { return (reg & 3) + 8 * (reg >> 2) + 4 * h; }
; #define MFMA32(a, b, c) __builtin_amdgcn_mfma_f32_32x32x16_bf16((a), (b), (c), 0, 0, 0)
; DI void nsa_item(unsigned char* ws_, const float* qg, const bf16_t* proj, bf16_t* mix, int item, LP unsigned char* lds3) {
;     ...
;   const float g0 = sigmf(bf2f(proj[tokrow + N_GT + (g * 4 + hd) * 3 + 0]));
;   const float g1 = sigmf(bf2f(proj[tokrow + N_GT + (g * 4 + hd) * 3 + 1]));
;   const float g2 = sigmf(bf2f(proj[tokrow + N_GT + (g * 4 + hd) * 3 + 2]));
;   __syncthreads();
;   { const bf16_t* kc = (const bf16_t*)(p.ws + WS_KCMP) + (size_t)bg * 128 * 64; const bf16_t* vc = (const bf16_t*)(p.ws + WS_VCMP) + (size_t)bg * 64 * 128;
; #pragma unroll
;     for (int i = 0; i < 2; ++i) { const int idx = tid + 512 * i; { const int n = idx >> 3, c = idx & 7; *(u32x4*)(Ks + n * 72 + c * 8) = *(const u32x4*)(kc + n * 64 + c * 8); }
;       { const int dd = idx >> 4, c = idx & 15; *(u32x4*)(VTs + dd * 136 + c * 8) = *(const u32x4*)(vc + dd * 128 + c * 8); } } }
;   __syncthreads();
;   {
;     f32x16 x[4]; float mx = NEGF;
; #pragma unroll
;     for (int sub = 0; sub < 4; ++sub) { x[sub] = zero16();
; #pragma unroll
;       for (int kk = 0; kk < 4; ++kk) x[sub] = MFMA32(*(const bf16x8*)(Ks + (sub * 32 + r) * 72 + kk * 16 + 8 * hh), qf[kk], x[sub]);
; #pragma unroll
;       for (int i = 0; i < 16; ++i) { const int n = sub * 32 + crow(i, hh); const bool ok = (n < 127) && (16 * n + 31 <= t);
;         x[sub][i] = ok ? x[sub][i] : NEGF; mx = fmaxf(mx, x[sub][i]); } }
	v_mfma_f32_32x32x16_bf16 v[16:31], v[32:35], v[72:75], v[16:31]
	ds_read_b128 v[32:35], v92 offset:9216
	ds_read_b128 v[48:51], v92 offset:9248
	s_waitcnt lgkmcnt(2)
	v_mfma_f32_32x32x16_bf16 v[16:31], v[36:39], v[76:79], v[16:31]
	s_waitcnt lgkmcnt(1)
	v_mfma_f32_32x32x16_bf16 v[32:47], v[32:35], v[64:67], 0
	s_waitcnt lgkmcnt(0)
	v_mfma_f32_32x32x16_bf16 v[32:47], v[48:51], v[68:71], v[32:47]
	ds_read_b128 v[48:51], v92 offset:9280
	ds_read_b128 v[52:55], v92 offset:9312
	s_waitcnt lgkmcnt(1)
	v_mfma_f32_32x32x16_bf16 v[32:47], v[48:51], v[72:75], v[32:47]
	ds_read_b128 v[48:51], v92 offset:13824
	ds_read_b128 v[80:83], v92 offset:13856
	ds_read_b128 v[112:115], v92 offset:13920
	s_waitcnt lgkmcnt(3)
	v_mfma_f32_32x32x16_bf16 v[32:47], v[52:55], v[76:79], v[32:47]
	s_waitcnt lgkmcnt(2)
	v_mfma_f32_32x32x16_bf16 v[48:63], v[48:51], v[64:67], 0
	s_waitcnt lgkmcnt(1)
	v_mfma_f32_32x32x16_bf16 v[48:63], v[80:83], v[68:71], v[48:63]
	ds_read_b128 v[80:83], v92 offset:13888
	s_waitcnt lgkmcnt(0)
	v_mfma_f32_32x32x16_bf16 v[48:63], v[80:83], v[72:75], v[48:63]
	v_lshlrev_b32_e32 v83, 6, v89
	v_mul_f32_e32 v80, 0xbfb8aa3b, v93
	v_subrev_u32_e32 v82, 31, v101
	v_or_b32_e32 v93, 16, v83
	v_cmp_le_i32_e32 vcc, v93, v82
	v_or_b32_e32 v95, 0x7a0, v83
	v_or_b32_e32 v96, 0x780, v83
	v_mfma_f32_32x32x16_bf16 v[48:63], v[112:115], v[76:79], v[48:63]
	v_cndmask_b32_e32 v1, v201, v1, vcc
	v_cmp_le_i32_e32 vcc, v83, v82
	v_exp_f32_e32 v80, v80
	s_nop 0
	v_cndmask_b32_e32 v0, v201, v0, vcc
	v_cmp_le_i32_e32 vcc, v95, v82
	v_or_b32_e32 v95, 0x7b0, v83
	v_add_f32_e32 v92, 1.0, v80
	s_nop 3
	v_cndmask_b32_e32 v62, v201, v62, vcc
	v_cmp_le_i32_e32 vcc, v95, v82
	s_and_b64 vcc, s[6:7], vcc
	v_or_b32_e32 v95, 0x790, v83
	v_cndmask_b32_e32 v63, v201, v63, vcc
	v_cmp_le_i32_e32 vcc, v95, v82
	v_or_b32_e32 v95, 0x730, v83
	v_div_scale_f32 v81, s[2:3], v92, v92, 1.0
	v_cndmask_b32_e32 v61, v201, v61, vcc
	v_cmp_le_i32_e32 vcc, v96, v82
	v_or_b32_e32 v96, 0x720, v83
	s_mov_b32 s2, 0xf149f2ca
	v_cndmask_b32_e32 v60, v201, v60, vcc
	v_cmp_le_i32_e32 vcc, v95, v82
	v_or_b32_e32 v95, 0x710, v83
	v_max3_f32 v93, v0, s2, v1
	v_cndmask_b32_e32 v59, v201, v59, vcc
	v_cmp_le_i32_e32 vcc, v96, v82
	v_or_b32_e32 v96, 0x700, v83
	v_rcp_f32_e32 v80, v81
	v_cndmask_b32_e32 v58, v201, v58, vcc
	v_cmp_le_i32_e32 vcc, v95, v82
	v_or_b32_e32 v95, 0x6b0, v83
	s_mov_b32 s2, 0xefa18f08
	v_cndmask_b32_e32 v57, v201, v57, vcc
	v_cmp_le_i32_e32 vcc, v96, v82
	v_or_b32_e32 v96, 0x6a0, v83
	s_nop 0
	v_cndmask_b32_e32 v56, v201, v56, vcc
	v_cmp_le_i32_e32 vcc, v95, v82
	v_or_b32_e32 v95, 0x690, v83
	s_nop 0
	v_cndmask_b32_e32 v55, v201, v55, vcc
	v_cmp_le_i32_e32 vcc, v96, v82
	v_or_b32_e32 v96, 0x680, v83
	s_nop 0
	v_cndmask_b32_e32 v54, v201, v54, vcc
	v_cmp_le_i32_e32 vcc, v95, v82
	v_or_b32_e32 v95, 0x630, v83
	s_nop 0
	v_cndmask_b32_e32 v53, v201, v53, vcc
	v_cmp_le_i32_e32 vcc, v96, v82
	v_or_b32_e32 v96, 0x620, v83
	s_nop 0
	v_cndmask_b32_e32 v52, v201, v52, vcc
	v_cmp_le_i32_e32 vcc, v95, v82
	v_or_b32_e32 v95, 0x610, v83
	s_nop 0
	v_cndmask_b32_e32 v51, v201, v51, vcc
	v_cmp_le_i32_e32 vcc, v96, v82
	v_or_b32_e32 v96, 0x600, v83
	s_nop 0
	v_cndmask_b32_e32 v50, v201, v50, vcc
	v_cmp_le_i32_e32 vcc, v95, v82
	v_or_b32_e32 v95, 0x5b0, v83
	s_nop 0
	v_cndmask_b32_e32 v49, v201, v49, vcc
	v_cmp_le_i32_e32 vcc, v96, v82
	v_or_b32_e32 v96, 0x5a0, v83
	s_nop 0
	v_cndmask_b32_e32 v48, v201, v48, vcc
	v_cmp_le_i32_e32 vcc, v95, v82
	v_or_b32_e32 v95, 0x590, v83
	s_nop 0
	v_cndmask_b32_e32 v47, v201, v47, vcc
	v_cmp_le_i32_e32 vcc, v96, v82
	v_or_b32_e32 v96, 0x580, v83
	s_nop 0
	v_cndmask_b32_e32 v46, v201, v46, vcc
	v_cmp_le_i32_e32 vcc, v95, v82
	v_or_b32_e32 v95, 0x530, v83
	s_nop 0
	v_cndmask_b32_e32 v45, v201, v45, vcc
	v_cmp_le_i32_e32 vcc, v96, v82
	v_or_b32_e32 v96, 0x520, v83
	s_nop 0
	v_cndmask_b32_e32 v44, v201, v44, vcc
	v_cmp_le_i32_e32 vcc, v95, v82
	s_nop 1
	v_cndmask_b32_e32 v95, v201, v43, vcc
	v_cmp_le_i32_e32 vcc, v96, v82
	v_or_b32_e32 v43, 0x500, v83
	s_nop 0
	v_cndmask_b32_e32 v96, v201, v42, vcc
	v_or_b32_e32 v42, 0x510, v83
	v_cmp_le_i32_e32 vcc, v42, v82
	s_nop 1
	v_cndmask_b32_e32 v42, v201, v41, vcc
	v_cmp_le_i32_e32 vcc, v43, v82
	v_or_b32_e32 v41, 0x4a0, v83
	s_nop 0
	v_cndmask_b32_e32 v97, v201, v40, vcc
	v_or_b32_e32 v40, 0x4b0, v83
	v_cmp_le_i32_e32 vcc, v40, v82
	s_nop 1
	v_cndmask_b32_e32 v40, v201, v39, vcc
	v_cmp_le_i32_e32 vcc, v41, v82
	v_or_b32_e32 v39, 0x480, v83
	s_nop 0
	v_cndmask_b32_e32 v43, v201, v38, vcc
	v_or_b32_e32 v38, 0x490, v83
	v_cmp_le_i32_e32 vcc, v38, v82
	s_nop 1
	v_cndmask_b32_e32 v38, v201, v37, vcc
	v_cmp_le_i32_e32 vcc, v39, v82
	v_or_b32_e32 v37, 0x420, v83
	s_nop 0
	v_cndmask_b32_e32 v41, v201, v36, vcc
	v_or_b32_e32 v36, 0x430, v83
	v_cmp_le_i32_e32 vcc, v36, v82
	s_nop 1
	v_cndmask_b32_e32 v36, v201, v35, vcc
	v_cmp_le_i32_e32 vcc, v37, v82
	v_or_b32_e32 v35, 0x400, v83
	v_fma_f32 v37, -v81, v80, 1.0
	v_cndmask_b32_e32 v39, v201, v34, vcc
	v_or_b32_e32 v34, 0x410, v83
	v_cmp_le_i32_e32 vcc, v34, v82
	v_or_b32_e32 v34, 0x3b0, v83
	v_fmac_f32_e32 v80, v37, v80
	v_cndmask_b32_e32 v33, v201, v33, vcc
	v_cmp_le_i32_e32 vcc, v35, v82
	v_or_b32_e32 v35, 0x3a0, v83
	s_nop 0
	v_cndmask_b32_e32 v32, v201, v32, vcc
	v_cmp_le_i32_e32 vcc, v34, v82
	v_or_b32_e32 v34, 0x390, v83
	s_nop 0
	v_cndmask_b32_e32 v31, v201, v31, vcc
	v_cmp_le_i32_e32 vcc, v35, v82
	v_or_b32_e32 v35, 0x380, v83
	s_nop 0
	v_cndmask_b32_e32 v30, v201, v30, vcc
	v_cmp_le_i32_e32 vcc, v34, v82
	v_or_b32_e32 v34, 0x330, v83
	s_nop 0
	v_cndmask_b32_e32 v29, v201, v29, vcc
	v_cmp_le_i32_e32 vcc, v35, v82
	v_or_b32_e32 v35, 0x320, v83
	s_nop 0
	v_cndmask_b32_e32 v28, v201, v28, vcc
; DI int crow(int reg, int h) { return (reg & 3) + 8 * (reg >> 2) + 4 * h; }
; DI void nsa_item(unsigned char* ws_, const float* qg, const bf16_t* proj, bf16_t* mix, int item, LP unsigned char* lds3) {
;     ...
;       for (int i = 0; i < 16; ++i) { const int n = sub * 32 + crow(i, hh); const bool ok = (n < 127) && (16 * n + 31 <= t);
;         x[sub][i] = ok ? x[sub][i] : NEGF; mx = fmaxf(mx, x[sub][i]); } }
;     mx = fmaxf(mx, __shfl_xor(mx, 32));
;     float ps = 0.f;
; #pragma unroll
;     for (int sub = 0; sub < 4; ++sub)
; #pragma unroll
;       for (int i = 0; i < 16; ++i) { const float pv = (x[sub][i] > -1e29f) ? __builtin_amdgcn_exp2f(x[sub][i] - mx) : 0.f; x[sub][i] = pv; ps += pv; }
	v_cmp_le_i32_e32 vcc, v34, v82
	v_or_b32_e32 v34, 0x310, v83
	s_nop 0
	v_cndmask_b32_e32 v27, v201, v27, vcc
	v_cmp_le_i32_e32 vcc, v35, v82
	v_or_b32_e32 v35, 0x300, v83
	s_nop 0
	v_cndmask_b32_e32 v26, v201, v26, vcc
	v_cmp_le_i32_e32 vcc, v34, v82
	v_or_b32_e32 v34, 0x2b0, v83
	s_nop 0
	v_cndmask_b32_e32 v25, v201, v25, vcc
	v_cmp_le_i32_e32 vcc, v35, v82
	v_or_b32_e32 v35, 0x2a0, v83
	s_nop 0
	v_cndmask_b32_e32 v24, v201, v24, vcc
	v_cmp_le_i32_e32 vcc, v34, v82
	v_or_b32_e32 v34, 0x290, v83
	s_nop 0
	v_cndmask_b32_e32 v23, v201, v23, vcc
	v_cmp_le_i32_e32 vcc, v35, v82
	v_or_b32_e32 v35, 0x280, v83
	s_nop 0
	v_cndmask_b32_e32 v22, v201, v22, vcc
	v_cmp_le_i32_e32 vcc, v34, v82
	v_or_b32_e32 v34, 0x230, v83
	s_nop 0
	v_cndmask_b32_e32 v21, v201, v21, vcc
	v_cmp_le_i32_e32 vcc, v35, v82
	v_or_b32_e32 v35, 0x220, v83
	s_nop 0
	v_cndmask_b32_e32 v20, v201, v20, vcc
	v_cmp_le_i32_e32 vcc, v34, v82
	v_or_b32_e32 v34, 0x210, v83
	s_nop 0
	v_cndmask_b32_e32 v19, v201, v19, vcc
	v_cmp_le_i32_e32 vcc, v35, v82
	v_or_b32_e32 v35, 0x200, v83
	s_nop 0
	v_cndmask_b32_e32 v18, v201, v18, vcc
	v_cmp_le_i32_e32 vcc, v34, v82
	v_or_b32_e32 v34, 0x1b0, v83
	s_nop 0
	v_cndmask_b32_e32 v17, v201, v17, vcc
	v_cmp_le_i32_e32 vcc, v35, v82
	v_or_b32_e32 v35, 0x1a0, v83
	s_nop 0
	v_cndmask_b32_e32 v16, v201, v16, vcc
	v_cmp_le_i32_e32 vcc, v34, v82
	v_or_b32_e32 v34, 0x190, v83
	s_nop 0
	v_cndmask_b32_e32 v15, v201, v15, vcc
	v_cmp_le_i32_e32 vcc, v35, v82
	v_or_b32_e32 v35, 0x180, v83
	s_nop 0
	v_cndmask_b32_e32 v14, v201, v14, vcc
	v_cmp_le_i32_e32 vcc, v34, v82
	v_or_b32_e32 v34, 0x130, v83
	s_nop 0
	v_cndmask_b32_e32 v13, v201, v13, vcc
	v_cmp_le_i32_e32 vcc, v35, v82
	v_or_b32_e32 v35, 0x120, v83
	s_nop 0
	v_cndmask_b32_e32 v12, v201, v12, vcc
	v_cmp_le_i32_e32 vcc, v34, v82
	v_or_b32_e32 v34, 0x110, v83
	s_nop 0
	v_cndmask_b32_e32 v11, v201, v11, vcc
	v_cmp_le_i32_e32 vcc, v35, v82
	v_or_b32_e32 v35, 0x100, v83
	s_nop 0
	v_cndmask_b32_e32 v10, v201, v10, vcc
	v_cmp_le_i32_e32 vcc, v34, v82
	v_or_b32_e32 v34, 0xb0, v83
	s_nop 0
	v_cndmask_b32_e32 v9, v201, v9, vcc
	v_cmp_le_i32_e32 vcc, v35, v82
	v_or_b32_e32 v35, 0xa0, v83
	s_nop 0
	v_cndmask_b32_e32 v8, v201, v8, vcc
	v_cmp_le_i32_e32 vcc, v34, v82
	v_or_b32_e32 v34, 0x90, v83
	s_nop 0
	v_cndmask_b32_e32 v7, v201, v7, vcc
	v_cmp_le_i32_e32 vcc, v35, v82
	v_or_b32_e32 v35, 0x80, v83
	s_nop 0
	v_cndmask_b32_e32 v6, v201, v6, vcc
	v_cmp_le_i32_e32 vcc, v34, v82
	v_or_b32_e32 v34, 48, v83
	s_nop 0
	v_cndmask_b32_e32 v5, v201, v5, vcc
	v_cmp_le_i32_e32 vcc, v35, v82
	v_or_b32_e32 v35, 32, v83
	s_nop 0
	v_cndmask_b32_e32 v4, v201, v4, vcc
	v_cmp_le_i32_e32 vcc, v34, v82
	s_nop 1
	v_cndmask_b32_e32 v3, v201, v3, vcc
	v_cmp_le_i32_e32 vcc, v35, v82
	s_nop 1
	v_cndmask_b32_e32 v2, v201, v2, vcc
	v_max3_f32 v34, v93, v2, v3
	v_max3_f32 v34, v34, v4, v5
	v_max3_f32 v34, v34, v6, v7
	v_max3_f32 v34, v34, v8, v9
	v_max3_f32 v34, v34, v10, v11
	v_max3_f32 v34, v34, v12, v13
	v_max3_f32 v34, v34, v14, v15
	v_max3_f32 v34, v34, v16, v17
	v_max3_f32 v34, v34, v18, v19
	v_max3_f32 v34, v34, v20, v21
	v_max3_f32 v34, v34, v22, v23
	v_max3_f32 v34, v34, v24, v25
	v_max3_f32 v34, v34, v26, v27
	v_max3_f32 v34, v34, v28, v29
	v_max3_f32 v34, v34, v30, v31
	v_max3_f32 v34, v34, v32, v33
	v_max3_f32 v34, v34, v39, v36
	v_max3_f32 v34, v34, v41, v38
	v_max3_f32 v34, v34, v43, v40
	v_max3_f32 v34, v34, v97, v42
	v_max3_f32 v34, v34, v96, v95
	v_max3_f32 v34, v34, v44, v45
	v_max3_f32 v34, v34, v46, v47
	v_max3_f32 v34, v34, v48, v49
	v_max3_f32 v34, v34, v50, v51
	v_max3_f32 v34, v34, v52, v53
	v_max3_f32 v34, v34, v54, v55
	v_max3_f32 v34, v34, v56, v57
	v_max3_f32 v34, v34, v58, v59
	v_max3_f32 v34, v34, v60, v61
	v_max3_f32 v34, v34, v62, v63
	ds_bpermute_b32 v35, v102, v34
	v_cmp_lt_f32_e32 vcc, s2, v1
	s_waitcnt lgkmcnt(0)
	v_max_f32_e32 v35, v35, v35
	v_max_f32_e32 v82, v34, v35
	v_sub_f32_e32 v34, v1, v82
	v_exp_f32_e32 v34, v34
	v_sub_f32_e32 v35, v0, v82
	v_exp_f32_e32 v35, v35
	v_sub_f32_e32 v37, v2, v82
	v_cndmask_b32_e32 v1, 0, v34, vcc
	v_cmp_lt_f32_e32 vcc, s2, v0
	v_exp_f32_e32 v37, v37
	s_nop 0
	v_cndmask_b32_e32 v0, 0, v35, vcc
	v_sub_f32_e32 v35, v3, v82
	v_exp_f32_e32 v35, v35
	v_cmp_lt_f32_e32 vcc, s2, v3
	v_add_f32_e32 v34, 0, v0
	v_add_f32_e32 v34, v1, v34
	v_cndmask_b32_e32 v3, 0, v35, vcc
	v_cmp_lt_f32_e32 vcc, s2, v2
	v_sub_f32_e32 v35, v5, v82
	v_exp_f32_e32 v35, v35
	v_cndmask_b32_e32 v2, 0, v37, vcc
	v_sub_f32_e32 v37, v4, v82
	v_exp_f32_e32 v37, v37
	v_cmp_lt_f32_e32 vcc, s2, v5
	v_add_f32_e32 v34, v2, v34
	v_add_f32_e32 v34, v3, v34
	v_cndmask_b32_e32 v5, 0, v35, vcc
	v_cmp_lt_f32_e32 vcc, s2, v4
	v_sub_f32_e32 v35, v7, v82
	v_exp_f32_e32 v35, v35
	v_cndmask_b32_e32 v4, 0, v37, vcc
	v_sub_f32_e32 v37, v6, v82
	v_exp_f32_e32 v37, v37
	v_cmp_lt_f32_e32 vcc, s2, v7
	v_add_f32_e32 v34, v4, v34
	v_add_f32_e32 v34, v5, v34
	v_cndmask_b32_e32 v7, 0, v35, vcc
	v_cmp_lt_f32_e32 vcc, s2, v6
	v_sub_f32_e32 v35, v9, v82
	v_exp_f32_e32 v35, v35
	v_cndmask_b32_e32 v6, 0, v37, vcc
	v_sub_f32_e32 v37, v8, v82
	v_exp_f32_e32 v37, v37
	v_cmp_lt_f32_e32 vcc, s2, v9
	v_add_f32_e32 v34, v6, v34
	v_add_f32_e32 v34, v7, v34
	v_cndmask_b32_e32 v9, 0, v35, vcc
	v_cmp_lt_f32_e32 vcc, s2, v8
	v_sub_f32_e32 v35, v11, v82
	v_exp_f32_e32 v35, v35
	v_cndmask_b32_e32 v8, 0, v37, vcc
	v_sub_f32_e32 v37, v10, v82
	v_exp_f32_e32 v37, v37
	v_cmp_lt_f32_e32 vcc, s2, v11
	v_add_f32_e32 v34, v8, v34
	v_add_f32_e32 v34, v9, v34
	v_cndmask_b32_e32 v11, 0, v35, vcc
	v_cmp_lt_f32_e32 vcc, s2, v10
	v_sub_f32_e32 v35, v13, v82
	v_exp_f32_e32 v35, v35
	v_cndmask_b32_e32 v10, 0, v37, vcc
	v_sub_f32_e32 v37, v12, v82
	v_exp_f32_e32 v37, v37
; DI void nsa_item(unsigned char* ws_, const float* qg, const bf16_t* proj, bf16_t* mix, int item, LP unsigned char* lds3) {
;     ...
;     float ps = 0.f;
; #pragma unroll
;     for (int sub = 0; sub < 4; ++sub)
; #pragma unroll
;       for (int i = 0; i < 16; ++i) { const float pv = (x[sub][i] > -1e29f) ? __builtin_amdgcn_exp2f(x[sub][i] - mx) : 0.f; x[sub][i] = pv; ps += pv; }
	v_cmp_lt_f32_e32 vcc, s2, v13
	v_add_f32_e32 v34, v10, v34
	v_add_f32_e32 v34, v11, v34
	v_cndmask_b32_e32 v13, 0, v35, vcc
	v_cmp_lt_f32_e32 vcc, s2, v12
	v_sub_f32_e32 v35, v15, v82
	v_exp_f32_e32 v35, v35
	v_cndmask_b32_e32 v12, 0, v37, vcc
	v_sub_f32_e32 v37, v14, v82
	v_exp_f32_e32 v37, v37
	v_cmp_lt_f32_e32 vcc, s2, v15
	v_add_f32_e32 v34, v12, v34
	v_add_f32_e32 v34, v13, v34
	v_cndmask_b32_e32 v15, 0, v35, vcc
	v_cmp_lt_f32_e32 vcc, s2, v14
	v_sub_f32_e32 v35, v17, v82
	v_exp_f32_e32 v35, v35
	v_cndmask_b32_e32 v14, 0, v37, vcc
	v_sub_f32_e32 v37, v16, v82
	v_exp_f32_e32 v37, v37
	v_cmp_lt_f32_e32 vcc, s2, v17
	v_add_f32_e32 v34, v14, v34
	v_add_f32_e32 v34, v15, v34
	v_cndmask_b32_e32 v17, 0, v35, vcc
	v_cmp_lt_f32_e32 vcc, s2, v16
	v_sub_f32_e32 v35, v19, v82
	v_exp_f32_e32 v35, v35
	v_cndmask_b32_e32 v16, 0, v37, vcc
	v_sub_f32_e32 v37, v18, v82
	v_exp_f32_e32 v37, v37
	v_cmp_lt_f32_e32 vcc, s2, v19
	v_add_f32_e32 v34, v16, v34
	v_add_f32_e32 v34, v17, v34
	v_cndmask_b32_e32 v19, 0, v35, vcc
	v_cmp_lt_f32_e32 vcc, s2, v18
	v_sub_f32_e32 v35, v21, v82
	v_exp_f32_e32 v35, v35
	v_cndmask_b32_e32 v18, 0, v37, vcc
	v_sub_f32_e32 v37, v20, v82
	v_exp_f32_e32 v37, v37
	v_cmp_lt_f32_e32 vcc, s2, v21
	v_add_f32_e32 v34, v18, v34
	v_add_f32_e32 v34, v19, v34
	v_cndmask_b32_e32 v21, 0, v35, vcc
	v_cmp_lt_f32_e32 vcc, s2, v20
	v_sub_f32_e32 v35, v23, v82
	v_exp_f32_e32 v35, v35
	v_cndmask_b32_e32 v20, 0, v37, vcc
	v_sub_f32_e32 v37, v22, v82
	v_exp_f32_e32 v37, v37
	v_cmp_lt_f32_e32 vcc, s2, v23
	v_add_f32_e32 v34, v20, v34
	v_add_f32_e32 v34, v21, v34
	v_cndmask_b32_e32 v23, 0, v35, vcc
	v_cmp_lt_f32_e32 vcc, s2, v22
	v_sub_f32_e32 v35, v25, v82
	v_exp_f32_e32 v35, v35
	v_cndmask_b32_e32 v22, 0, v37, vcc
	v_sub_f32_e32 v37, v24, v82
	v_exp_f32_e32 v37, v37
	v_cmp_lt_f32_e32 vcc, s2, v25
	v_add_f32_e32 v34, v22, v34
	v_add_f32_e32 v34, v23, v34
	v_cndmask_b32_e32 v25, 0, v35, vcc
	v_cmp_lt_f32_e32 vcc, s2, v24
	v_sub_f32_e32 v35, v27, v82
	v_exp_f32_e32 v35, v35
	v_cndmask_b32_e32 v24, 0, v37, vcc
	v_sub_f32_e32 v37, v26, v82
	v_exp_f32_e32 v37, v37
	v_cmp_lt_f32_e32 vcc, s2, v27
	v_add_f32_e32 v34, v24, v34
	v_add_f32_e32 v34, v25, v34
	v_cndmask_b32_e32 v27, 0, v35, vcc
	v_cmp_lt_f32_e32 vcc, s2, v26
	v_sub_f32_e32 v35, v29, v82
	v_exp_f32_e32 v35, v35
	v_cndmask_b32_e32 v26, 0, v37, vcc
	v_sub_f32_e32 v37, v28, v82
	v_exp_f32_e32 v37, v37
	v_cmp_lt_f32_e32 vcc, s2, v29
	v_add_f32_e32 v34, v26, v34
	v_add_f32_e32 v34, v27, v34
	v_cndmask_b32_e32 v29, 0, v35, vcc
	v_cmp_lt_f32_e32 vcc, s2, v28
	v_sub_f32_e32 v35, v31, v82
	v_exp_f32_e32 v35, v35
	v_cndmask_b32_e32 v28, 0, v37, vcc
	v_sub_f32_e32 v37, v30, v82
	v_exp_f32_e32 v37, v37
	v_cmp_lt_f32_e32 vcc, s2, v31
	v_add_f32_e32 v34, v28, v34
	v_add_f32_e32 v34, v29, v34
	v_cndmask_b32_e32 v31, 0, v35, vcc
	v_cmp_lt_f32_e32 vcc, s2, v30
	v_sub_f32_e32 v35, v32, v82
	v_exp_f32_e32 v83, v35
	v_cndmask_b32_e32 v30, 0, v37, vcc
	v_add_f32_e32 v34, v30, v34
	v_add_f32_e32 v37, v31, v34
	v_sub_f32_e32 v34, v33, v82
	v_exp_f32_e32 v34, v34
	v_cmp_lt_f32_e32 vcc, s2, v33
	v_sub_f32_e32 v33, v36, v82
	v_exp_f32_e32 v33, v33
	v_cndmask_b32_e32 v35, 0, v34, vcc
	v_cmp_lt_f32_e32 vcc, s2, v32
	s_nop 1
	v_cndmask_b32_e32 v34, 0, v83, vcc
	v_add_f32_e32 v32, v34, v37
	v_sub_f32_e32 v37, v39, v82
	v_cmp_lt_f32_e32 vcc, s2, v36
	v_exp_f32_e32 v83, v37
	v_add_f32_e32 v32, v35, v32
	v_cndmask_b32_e32 v37, 0, v33, vcc
	v_sub_f32_e32 v33, v38, v82
	v_exp_f32_e32 v33, v33
	v_cmp_lt_f32_e32 vcc, s2, v39
	v_sub_f32_e32 v39, v41, v82
	s_nop 0
	v_cndmask_b32_e32 v36, 0, v83, vcc
	v_cmp_lt_f32_e32 vcc, s2, v38
	v_exp_f32_e32 v83, v39
	v_add_f32_e32 v32, v36, v32
	v_cndmask_b32_e32 v39, 0, v33, vcc
	v_sub_f32_e32 v33, v40, v82
	v_exp_f32_e32 v33, v33
	v_cmp_lt_f32_e32 vcc, s2, v41
	v_sub_f32_e32 v41, v43, v82
	v_add_f32_e32 v32, v37, v32
	v_cndmask_b32_e32 v38, 0, v83, vcc
	v_cmp_lt_f32_e32 vcc, s2, v40
	v_exp_f32_e32 v83, v41
	v_add_f32_e32 v32, v38, v32
	v_cndmask_b32_e32 v41, 0, v33, vcc
	v_sub_f32_e32 v33, v42, v82
	v_exp_f32_e32 v33, v33
	v_cmp_lt_f32_e32 vcc, s2, v43
	v_sub_f32_e32 v43, v97, v82
	v_add_f32_e32 v32, v39, v32
	v_cndmask_b32_e32 v40, 0, v83, vcc
	v_cmp_lt_f32_e32 vcc, s2, v42
	v_exp_f32_e32 v83, v43
	v_add_f32_e32 v32, v40, v32
	v_cndmask_b32_e32 v43, 0, v33, vcc
	v_sub_f32_e32 v33, v95, v82
	v_exp_f32_e32 v33, v33
	v_cmp_lt_f32_e32 vcc, s2, v97
	v_add_f32_e32 v32, v41, v32
	s_nop 0
	v_cndmask_b32_e32 v42, 0, v83, vcc
	v_sub_f32_e32 v83, v96, v82
	v_cmp_lt_f32_e32 vcc, s2, v95
	v_exp_f32_e32 v83, v83
	v_add_f32_e32 v32, v42, v32
	v_cndmask_b32_e32 v97, 0, v33, vcc
	v_sub_f32_e32 v33, v45, v82
	v_exp_f32_e32 v33, v33
	v_cmp_lt_f32_e32 vcc, s2, v96
	v_add_f32_e32 v32, v43, v32
	s_nop 0
	v_cndmask_b32_e32 v96, 0, v83, vcc
	v_sub_f32_e32 v83, v44, v82
	v_cmp_lt_f32_e32 vcc, s2, v45
	v_exp_f32_e32 v83, v83
	v_add_f32_e32 v32, v96, v32
	v_cndmask_b32_e32 v45, 0, v33, vcc
	v_sub_f32_e32 v33, v47, v82
	v_exp_f32_e32 v33, v33
	v_cmp_lt_f32_e32 vcc, s2, v44
	v_add_f32_e32 v32, v97, v32
	s_nop 0
	v_cndmask_b32_e32 v44, 0, v83, vcc
	v_sub_f32_e32 v83, v46, v82
	v_cmp_lt_f32_e32 vcc, s2, v47
	v_exp_f32_e32 v83, v83
	v_add_f32_e32 v32, v44, v32
	v_cndmask_b32_e32 v47, 0, v33, vcc
	v_sub_f32_e32 v33, v49, v82
	v_exp_f32_e32 v33, v33
	v_cmp_lt_f32_e32 vcc, s2, v46
	v_add_f32_e32 v32, v45, v32
	s_nop 0
	v_cndmask_b32_e32 v46, 0, v83, vcc
	v_sub_f32_e32 v83, v48, v82
	v_cmp_lt_f32_e32 vcc, s2, v49
	v_exp_f32_e32 v83, v83
	v_add_f32_e32 v32, v46, v32
	v_cndmask_b32_e32 v105, 0, v33, vcc
	v_sub_f32_e32 v33, v51, v82
	v_cmp_lt_f32_e32 vcc, s2, v48
	v_exp_f32_e32 v33, v33
	v_sub_f32_e32 v48, v50, v82
; DI void nsa_item(unsigned char* ws_, const float* qg, const bf16_t* proj, bf16_t* mix, int item, LP unsigned char* lds3) {
;     ...
;       for (int i = 0; i < 16; ++i) { const float pv = (x[sub][i] > -1e29f) ? __builtin_amdgcn_exp2f(x[sub][i] - mx) : 0.f; x[sub][i] = pv; ps += pv; }
;     ps += __shfl_xor(ps, 32);
;     const float inv = ps > 0.f ? 1.f / ps : 0.f;
;     float Gs[16], last[16];
; #pragma unroll
;     for (int sub = 0; sub < 4; ++sub)
; #pragma unroll
;       for (int gq = 0; gq < 4; ++gq) {
; #pragma unroll
;         for (int e = 0; e < 4; ++e) x[sub][4 * gq + e] *= inv;
;         Gs[sub * 4 + gq] = (x[sub][4 * gq] + x[sub][4 * gq + 1]) + (x[sub][4 * gq + 2] + x[sub][4 * gq + 3]); last[sub * 4 + gq] = x[sub][4 * gq + 3]; }
; #pragma unroll
;     for (int mi = 0; mi < 16; ++mi) { const float rc = __shfl_xor(last[mi], 32); const float rp = (mi > 0) ? __shfl_xor(last[mi > 0 ? mi - 1 : 0], 32) : 0.f;
;       imp[(hd * 64 + tl) * 32 + 2 * mi + hh] = Gs[mi] + (hh ? rc : rp); }
	v_exp_f32_e32 v48, v48
	v_cndmask_b32_e32 v104, 0, v83, vcc
	v_cmp_lt_f32_e32 vcc, s2, v51
	v_add_f32_e32 v32, v47, v32
	v_add_f32_e32 v32, v104, v32
	v_cndmask_b32_e32 v113, 0, v33, vcc
	v_cmp_lt_f32_e32 vcc, s2, v50
	v_sub_f32_e32 v33, v53, v82
	v_exp_f32_e32 v33, v33
	v_cndmask_b32_e32 v112, 0, v48, vcc
	v_sub_f32_e32 v48, v52, v82
	v_exp_f32_e32 v48, v48
	v_cmp_lt_f32_e32 vcc, s2, v53
	v_add_f32_e32 v32, v105, v32
	v_add_f32_e32 v32, v112, v32
	v_cndmask_b32_e32 v115, 0, v33, vcc
	v_cmp_lt_f32_e32 vcc, s2, v52
	v_sub_f32_e32 v33, v55, v82
	v_exp_f32_e32 v33, v33
	v_cndmask_b32_e32 v114, 0, v48, vcc
	v_sub_f32_e32 v48, v54, v82
	v_exp_f32_e32 v48, v48
	v_cmp_lt_f32_e32 vcc, s2, v55
	v_add_f32_e32 v32, v113, v32
	v_add_f32_e32 v32, v114, v32
	v_cndmask_b32_e32 v117, 0, v33, vcc
	v_cmp_lt_f32_e32 vcc, s2, v54
	v_sub_f32_e32 v33, v57, v82
	v_exp_f32_e32 v33, v33
	v_cndmask_b32_e32 v116, 0, v48, vcc
	v_sub_f32_e32 v48, v56, v82
	v_exp_f32_e32 v48, v48
	v_cmp_lt_f32_e32 vcc, s2, v57
	v_add_f32_e32 v32, v115, v32
	v_add_f32_e32 v32, v116, v32
	v_cndmask_b32_e32 v119, 0, v33, vcc
	v_cmp_lt_f32_e32 vcc, s2, v56
	v_sub_f32_e32 v33, v59, v82
	v_exp_f32_e32 v33, v33
	v_cndmask_b32_e32 v118, 0, v48, vcc
	v_sub_f32_e32 v48, v58, v82
	v_exp_f32_e32 v48, v48
	v_cmp_lt_f32_e32 vcc, s2, v59
	v_add_f32_e32 v32, v117, v32
	v_add_f32_e32 v32, v118, v32
	v_cndmask_b32_e32 v121, 0, v33, vcc
	v_cmp_lt_f32_e32 vcc, s2, v58
	v_sub_f32_e32 v33, v61, v82
	v_exp_f32_e32 v33, v33
	v_cndmask_b32_e32 v120, 0, v48, vcc
	v_sub_f32_e32 v48, v60, v82
	v_exp_f32_e32 v48, v48
	v_cmp_lt_f32_e32 vcc, s2, v61
	v_add_f32_e32 v32, v119, v32
	v_add_f32_e32 v32, v120, v32
	v_cndmask_b32_e32 v123, 0, v33, vcc
	v_cmp_lt_f32_e32 vcc, s2, v60
	v_sub_f32_e32 v33, v62, v82
	v_exp_f32_e32 v33, v33
	v_cndmask_b32_e32 v122, 0, v48, vcc
	v_sub_f32_e32 v48, v63, v82
	v_exp_f32_e32 v48, v48
	v_add_f32_e32 v32, v121, v32
	v_add_f32_e32 v32, v122, v32
	v_cmp_lt_f32_e32 vcc, s2, v62
	v_add_f32_e32 v32, v123, v32
	s_nop 0
	v_cndmask_b32_e32 v33, 0, v33, vcc
	v_cmp_lt_f32_e32 vcc, s2, v63
	v_add_f32_e32 v32, v33, v32
	s_nop 0
	v_cndmask_b32_e32 v93, 0, v48, vcc
	v_add_f32_e32 v32, v93, v32
	ds_bpermute_b32 v48, v102, v32
	v_div_scale_f32 v49, vcc, 1.0, v92, 1.0
	v_mul_f32_e32 v50, v49, v80
	v_fma_f32 v51, -v81, v50, v49
	s_waitcnt lgkmcnt(0)
	v_add_f32_e32 v32, v32, v48
	v_div_scale_f32 v48, s[2:3], v32, v32, 1.0
	v_fmac_f32_e32 v50, v51, v80
	v_rcp_f32_e32 v51, v48
	v_fma_f32 v49, -v81, v50, v49
	v_div_fmas_f32 v95, v49, v80, v50
	v_fma_f32 v49, -v48, v51, 1.0
	v_fmac_f32_e32 v51, v49, v51
	v_div_scale_f32 v49, vcc, 1.0, v32, 1.0
	v_mul_f32_e32 v50, v49, v51
	v_fma_f32 v52, -v48, v50, v49
	v_fmac_f32_e32 v50, v52, v51
	v_fma_f32 v48, -v48, v50, v49
	v_div_fmas_f32 v48, v48, v51, v50
	v_div_fixup_f32 v48, v48, v32, 1.0
	v_cmp_lt_f32_e32 vcc, 0, v32
	s_nop 1
	v_cndmask_b32_e32 v32, 0, v48, vcc
	v_pk_mul_f32 v[4:5], v[4:5], v[32:33] op_sel_hi:[1,0]
	v_pk_mul_f32 v[6:7], v[6:7], v[32:33] op_sel_hi:[1,0]
	v_pk_mul_f32 v[124:125], v[0:1], v[32:33] op_sel_hi:[1,0]
	v_add_f32_e32 v0, v6, v7
	v_add_f32_e32 v1, v4, v5
	v_pk_mul_f32 v[128:129], v[8:9], v[32:33] op_sel_hi:[1,0]
	v_pk_mul_f32 v[130:131], v[10:11], v[32:33] op_sel_hi:[1,0]
	v_pk_mul_f32 v[126:127], v[2:3], v[32:33] op_sel_hi:[1,0]
	v_add_f32_e32 v0, v1, v0
	v_add_f32_e32 v1, v130, v131
	v_add_f32_e32 v2, v128, v129
	v_pk_mul_f32 v[132:133], v[12:13], v[32:33] op_sel_hi:[1,0]
	v_pk_mul_f32 v[134:135], v[14:15], v[32:33] op_sel_hi:[1,0]
	v_add_f32_e32 v1, v2, v1
	v_add_f32_e32 v2, v134, v135
	v_add_f32_e32 v3, v132, v133
	v_pk_mul_f32 v[136:137], v[16:17], v[32:33] op_sel_hi:[1,0]
	v_pk_mul_f32 v[138:139], v[18:19], v[32:33] op_sel_hi:[1,0]
	v_add_f32_e32 v2, v3, v2
	v_add_f32_e32 v3, v138, v139
	v_add_f32_e32 v8, v136, v137
	v_pk_mul_f32 v[140:141], v[20:21], v[32:33] op_sel_hi:[1,0]
	v_pk_mul_f32 v[142:143], v[22:23], v[32:33] op_sel_hi:[1,0]
	v_add_f32_e32 v3, v8, v3
	v_add_f32_e32 v8, v142, v143
	v_add_f32_e32 v9, v140, v141
	v_pk_mul_f32 v[80:81], v[24:25], v[32:33] op_sel_hi:[1,0]
	v_pk_mul_f32 v[82:83], v[26:27], v[32:33] op_sel_hi:[1,0]
	v_add_f32_e32 v8, v9, v8
	v_add_f32_e32 v9, v82, v83
	v_add_f32_e32 v10, v80, v81
	v_pk_mul_f32 v[144:145], v[28:29], v[32:33] op_sel_hi:[1,0]
	v_pk_mul_f32 v[146:147], v[30:31], v[32:33] op_sel_hi:[1,0]
	v_add_f32_e32 v9, v10, v9
	v_add_f32_e32 v10, v146, v147
	v_add_f32_e32 v11, v144, v145
	v_pk_mul_f32 v[56:57], v[34:35], v[32:33] op_sel_hi:[1,0]
	v_pk_mul_f32 v[58:59], v[36:37], v[32:33] op_sel_hi:[1,0]
	v_add_f32_e32 v10, v11, v10
	v_add_f32_e32 v11, v58, v59
	v_add_f32_e32 v12, v56, v57
	v_pk_mul_f32 v[60:61], v[38:39], v[32:33] op_sel_hi:[1,0]
	v_pk_mul_f32 v[62:63], v[40:41], v[32:33] op_sel_hi:[1,0]
	v_add_f32_e32 v11, v12, v11
	v_add_f32_e32 v12, v62, v63
	v_add_f32_e32 v13, v60, v61
	v_pk_mul_f32 v[48:49], v[42:43], v[32:33] op_sel_hi:[1,0]
	v_pk_mul_f32 v[50:51], v[96:97], v[32:33] op_sel_hi:[1,0]
	v_add_f32_e32 v12, v13, v12
	v_add_f32_e32 v13, v50, v51
	v_add_f32_e32 v14, v48, v49
	v_pk_mul_f32 v[52:53], v[44:45], v[32:33] op_sel_hi:[1,0]
	v_pk_mul_f32 v[54:55], v[46:47], v[32:33] op_sel_hi:[1,0]
	v_add_f32_e32 v13, v14, v13
	v_add_f32_e32 v14, v54, v55
	v_add_f32_e32 v15, v52, v53
	v_pk_mul_f32 v[40:41], v[104:105], v[32:33] op_sel_hi:[1,0]
	v_pk_mul_f32 v[42:43], v[112:113], v[32:33] op_sel_hi:[1,0]
	v_add_f32_e32 v14, v15, v14
	v_add_f32_e32 v15, v42, v43
	v_add_f32_e32 v16, v40, v41
	v_pk_mul_f32 v[44:45], v[114:115], v[32:33] op_sel_hi:[1,0]
	v_pk_mul_f32 v[46:47], v[116:117], v[32:33] op_sel_hi:[1,0]
	v_add_f32_e32 v15, v16, v15
	v_add_f32_e32 v16, v46, v47
	v_add_f32_e32 v17, v44, v45
	v_pk_mul_f32 v[34:35], v[118:119], v[32:33] op_sel_hi:[1,0]
	v_pk_mul_f32 v[36:37], v[120:121], v[32:33] op_sel_hi:[1,0]
	v_add_f32_e32 v16, v17, v16
	v_add_f32_e32 v17, v36, v37
	v_add_f32_e32 v18, v34, v35
	v_pk_mul_f32 v[38:39], v[122:123], v[32:33] op_sel_hi:[1,0]
	v_mul_f32_e32 v93, v93, v32
	v_add_f32_e32 v17, v18, v17
	v_add_f32_e32 v18, v38, v39
	v_fma_f32 v19, v33, v32, v93
	v_add_f32_e32 v18, v18, v19
	v_lshl_add_u32 v19, v91, 13, 32
	v_lshlrev_b32_e32 v20, 7, v109
	v_lshlrev_b32_e32 v104, 2, v89
	v_add3_u32 v19, v19, v20, v104
	ds_bpermute_b32 v20, v102, v127
	ds_bpermute_b32 v22, v102, v7
	v_add_f32_e32 v21, v126, v127
	v_add_f32_e32 v23, v124, v125
	v_add_f32_e32 v21, v23, v21
	s_waitcnt lgkmcnt(1)
; #define MFMA32(a, b, c) __builtin_amdgcn_mfma_f32_32x32x16_bf16((a), (b), (c), 0, 0, 0)
; DI void nsa_item(unsigned char* ws_, const float* qg, const bf16_t* proj, bf16_t* mix, int item, LP unsigned char* lds3) {
;     ...
; #pragma unroll
;     for (int mi = 0; mi < 16; ++mi) { const float rc = __shfl_xor(last[mi], 32); const float rp = (mi > 0) ? __shfl_xor(last[mi > 0 ? mi - 1 : 0], 32) : 0.f;
;       imp[(hd * 64 + tl) * 32 + 2 * mi + hh] = Gs[mi] + (hh ? rc : rp); }
;     f32x16 comb[2]; comb[0] = zero16(); comb[1] = zero16();
; #pragma unroll
;     for (int sub = 0; sub < 4; ++sub)
; #pragma unroll
;       for (int s2 = 0; s2 < 2; ++s2) {
;         const bf16x8 pb = pack8(x[sub][8 * s2], x[sub][8 * s2 + 1], x[sub][8 * s2 + 2], x[sub][8 * s2 + 3], x[sub][8 * s2 + 4], x[sub][8 * s2 + 5], x[sub][8 * s2 + 6], x[sub][8 * s2 + 7]);
; #pragma unroll
;         for (int dt = 0; dt < 2; ++dt) { const bf16_t* vp = VTs + (dt * 32 + r) * 136 + sub * 32 + 16 * s2 + 4 * hh;
;           const s16x4 lo = *(const s16x4*)vp, hi = *(const s16x4*)(vp + 8);
;           const bf16x8 va = __builtin_shufflevector(lo, hi, 0, 1, 2, 3, 4, 5, 6, 7);
;           comb[dt] = MFMA32(va, pb, comb[dt]); } }
	v_cndmask_b32_e64 v23, v20, 0, s[6:7]
	v_add_f32_e32 v21, v23, v21
	s_waitcnt lgkmcnt(0)
	v_cndmask_b32_e64 v20, v22, v20, s[6:7]
	ds_bpermute_b32 v23, v102, v131
	v_add_f32_e32 v0, v0, v20
	ds_bpermute_b32 v20, v102, v135
	v_add_u32_e32 v19, 0x8c00, v19
	ds_write2_b32 v19, v21, v0 offset1:2
	s_waitcnt lgkmcnt(2)
	v_cndmask_b32_e64 v0, v23, v22, s[6:7]
	v_add_f32_e32 v0, v1, v0
	ds_bpermute_b32 v1, v102, v139
	s_waitcnt lgkmcnt(2)
	v_cndmask_b32_e64 v21, v20, v23, s[6:7]
	v_add_f32_e32 v2, v2, v21
	ds_bpermute_b32 v21, v102, v143
	ds_write2_b32 v19, v0, v2 offset0:4 offset1:6
	s_waitcnt lgkmcnt(2)
	v_cndmask_b32_e64 v0, v1, v20, s[6:7]
	v_add_f32_e32 v0, v3, v0
	ds_bpermute_b32 v2, v102, v83
	s_waitcnt lgkmcnt(2)
	v_cndmask_b32_e64 v1, v21, v1, s[6:7]
	ds_bpermute_b32 v3, v102, v147
	v_add_f32_e32 v1, v8, v1
	ds_write2_b32 v19, v0, v1 offset0:8 offset1:10
	ds_bpermute_b32 v1, v102, v59
	ds_bpermute_b32 v8, v102, v63
	s_waitcnt lgkmcnt(4)
	v_cndmask_b32_e64 v0, v2, v21, s[6:7]
	s_waitcnt lgkmcnt(3)
	v_cndmask_b32_e64 v2, v3, v2, s[6:7]
	v_add_f32_e32 v0, v9, v0
	v_add_f32_e32 v2, v10, v2
	ds_write2_b32 v19, v0, v2 offset0:12 offset1:14
	s_waitcnt lgkmcnt(2)
	v_cndmask_b32_e64 v0, v1, v3, s[6:7]
	ds_bpermute_b32 v2, v102, v51
	s_waitcnt lgkmcnt(2)
	v_cndmask_b32_e64 v1, v8, v1, s[6:7]
	ds_bpermute_b32 v3, v102, v55
	v_add_f32_e32 v0, v11, v0
	v_add_f32_e32 v1, v12, v1
	ds_write2_b32 v19, v0, v1 offset0:16 offset1:18
	ds_bpermute_b32 v1, v102, v43
	s_waitcnt lgkmcnt(3)
	v_cndmask_b32_e64 v0, v2, v8, s[6:7]
	s_waitcnt lgkmcnt(2)
	v_cndmask_b32_e64 v2, v3, v2, s[6:7]
	ds_bpermute_b32 v8, v102, v47
	v_add_f32_e32 v0, v13, v0
	v_add_f32_e32 v2, v14, v2
	ds_write2_b32 v19, v0, v2 offset0:20 offset1:22
	s_waitcnt lgkmcnt(2)
	v_cndmask_b32_e64 v0, v1, v3, s[6:7]
	ds_bpermute_b32 v2, v102, v37
	ds_bpermute_b32 v3, v102, v93
	s_waitcnt lgkmcnt(3)
	v_cndmask_b32_e64 v1, v8, v1, s[6:7]
	v_add_f32_e32 v0, v15, v0
	v_add_f32_e32 v1, v16, v1
	ds_write2_b32 v19, v0, v1 offset0:24 offset1:26
	s_waitcnt lgkmcnt(2)
	v_cndmask_b32_e64 v0, v2, v8, s[6:7]
	s_waitcnt lgkmcnt(1)
	v_cndmask_b32_e64 v1, v3, v2, s[6:7]
	v_lshl_add_u32 v112, v89, 3, 32
	v_add_f32_e32 v0, v17, v0
	v_add_f32_e32 v1, v18, v1
	v_mad_u32_u24 v20, v90, s5, v112
	ds_write2_b32 v19, v0, v1 offset0:28 offset1:30
	v_add_u32_e32 v89, 0x4800, v20
	ds_read2_b64 v[0:3], v89 offset1:2
	v_cvt_pk_bf16_f32 v16, v124, v125
	v_cvt_pk_bf16_f32 v17, v126, v127
	v_cvt_pk_bf16_f32 v18, v4, v5
	v_cvt_pk_bf16_f32 v19, v6, v7
	v_add_u32_e32 v91, 0x6800, v20
	ds_read2_b64 v[114:117], v89 offset0:4 offset1:6
	s_waitcnt lgkmcnt(1)
	v_mfma_f32_32x32x16_bf16 v[0:15], v[0:3], v[16:19], 0
	ds_read2_b64 v[20:23], v91 offset0:64 offset1:66
	v_cvt_pk_bf16_f32 v118, v128, v129
	v_cvt_pk_bf16_f32 v119, v130, v131
	v_cvt_pk_bf16_f32 v120, v132, v133
	v_cvt_pk_bf16_f32 v121, v134, v135
	v_cvt_pk_bf16_f32 v80, v80, v81
	v_cvt_pk_bf16_f32 v81, v82, v83
	s_waitcnt lgkmcnt(1)
	v_mfma_f32_32x32x16_bf16 v[0:15], v[114:117], v[118:121], v[0:15]
	ds_read2_b64 v[114:117], v91 offset0:68 offset1:70
	v_cvt_pk_bf16_f32 v82, v144, v145
	v_cvt_pk_bf16_f32 v83, v146, v147
	v_cvt_pk_bf16_f32 v56, v56, v57
	v_cvt_pk_bf16_f32 v57, v58, v59
	v_cvt_pk_bf16_f32 v58, v60, v61
	v_cvt_pk_bf16_f32 v59, v62, v63
	s_waitcnt lgkmcnt(1)
	v_mfma_f32_32x32x16_bf16 v[16:31], v[20:23], v[16:19], 0
	ds_read2_b64 v[60:63], v91 offset0:80 offset1:82
	v_cvt_pk_bf16_f32 v48, v48, v49
	v_cvt_pk_bf16_f32 v49, v50, v51
	v_cvt_pk_bf16_f32 v50, v52, v53
	v_cvt_pk_bf16_f32 v51, v54, v55
	ds_read2_b64 v[52:55], v91 offset0:84 offset1:86
	v_cvt_pk_bf16_f32 v40, v40, v41
	s_waitcnt lgkmcnt(2)
	v_mfma_f32_32x32x16_bf16 v[16:31], v[114:117], v[118:121], v[16:31]
	ds_read2_b64 v[114:117], v89 offset0:8 offset1:10
	v_cvt_pk_bf16_f32 v118, v136, v137
	v_cvt_pk_bf16_f32 v119, v138, v139
	v_cvt_pk_bf16_f32 v120, v140, v141
	v_cvt_pk_bf16_f32 v121, v142, v143
	v_cvt_pk_bf16_f32 v41, v42, v43
	v_cvt_pk_bf16_f32 v42, v44, v45
	s_waitcnt lgkmcnt(0)
; #define MFMA32(a, b, c) __builtin_amdgcn_mfma_f32_32x32x16_bf16((a), (b), (c), 0, 0, 0)
; DI void nsa_item(unsigned char* ws_, const float* qg, const bf16_t* proj, bf16_t* mix, int item, LP unsigned char* lds3) {
;     ...
;     f32x16 comb[2]; comb[0] = zero16(); comb[1] = zero16();
; #pragma unroll
;     for (int sub = 0; sub < 4; ++sub)
; #pragma unroll
;       for (int s2 = 0; s2 < 2; ++s2) {
;         const bf16x8 pb = pack8(x[sub][8 * s2], x[sub][8 * s2 + 1], x[sub][8 * s2 + 2], x[sub][8 * s2 + 3], x[sub][8 * s2 + 4], x[sub][8 * s2 + 5], x[sub][8 * s2 + 6], x[sub][8 * s2 + 7]);
; #pragma unroll
;         for (int dt = 0; dt < 2; ++dt) { const bf16_t* vp = VTs + (dt * 32 + r) * 136 + sub * 32 + 16 * s2 + 4 * hh;
;           const s16x4 lo = *(const s16x4*)vp, hi = *(const s16x4*)(vp + 8);
;           const bf16x8 va = __builtin_shufflevector(lo, hi, 0, 1, 2, 3, 4, 5, 6, 7);
;           comb[dt] = MFMA32(va, pb, comb[dt]); } }
; #pragma unroll
;     for (int i = 0; i < 16; ++i) { cmb[i * 512] = comb[0][i] * g0; cmb[(16 + i) * 512] = comb[1][i] * g0; }
;   }
;   if (tid < 64) msk[tid] = (qt < 16) ? ((qt == 31) ? 0xffffffffu : ((1u << (qt + 1)) - 1u)) : (1u | (1u << qt) | (1u << (qt - 1)));
	v_mfma_f32_32x32x16_bf16 v[0:15], v[114:117], v[118:121], v[0:15]
	ds_read2_b64 v[114:117], v91 offset0:72 offset1:74
	v_cvt_pk_bf16_f32 v43, v46, v47
	ds_read2_b64 v[44:47], v91 offset0:88 offset1:90
	v_mul_f32_e32 v32, v33, v32
	v_cvt_pk_bf16_f32 v34, v34, v35
	v_cvt_pk_bf16_f32 v35, v36, v37
	v_cvt_pk_bf16_f32 v36, v38, v39
	s_waitcnt lgkmcnt(1)
	v_mfma_f32_32x32x16_bf16 v[16:31], v[114:117], v[118:121], v[16:31]
	ds_read2_b64 v[114:117], v89 offset0:12 offset1:14
	v_cvt_pk_bf16_f32 v37, v32, v93
	v_lshl_add_u32 v32, v84, 2, 32
	v_div_fixup_f32 v33, v95, v92, 1.0
	v_add_u32_e32 v105, 0x11000, v32
	v_cmp_gt_i32_e32 vcc, 64, v84
	s_waitcnt lgkmcnt(0)
	v_mfma_f32_32x32x16_bf16 v[0:15], v[114:117], v[80:83], v[0:15]
	ds_read2_b64 v[114:117], v91 offset0:76 offset1:78
	s_waitcnt lgkmcnt(0)
	v_mfma_f32_32x32x16_bf16 v[16:31], v[114:117], v[80:83], v[16:31]
	ds_read2_b64 v[80:83], v89 offset0:16 offset1:18
	s_waitcnt lgkmcnt(0)
	v_mfma_f32_32x32x16_bf16 v[0:15], v[80:83], v[56:59], v[0:15]
	v_mfma_f32_32x32x16_bf16 v[16:31], v[60:63], v[56:59], v[16:31]
	ds_read2_b64 v[56:59], v89 offset0:20 offset1:22
	s_waitcnt lgkmcnt(0)
	v_mfma_f32_32x32x16_bf16 v[0:15], v[56:59], v[48:51], v[0:15]
	v_mfma_f32_32x32x16_bf16 v[16:31], v[52:55], v[48:51], v[16:31]
	ds_read2_b64 v[48:51], v89 offset0:24 offset1:26
	s_waitcnt lgkmcnt(0)
	v_mfma_f32_32x32x16_bf16 v[0:15], v[48:51], v[40:43], v[0:15]
	v_mfma_f32_32x32x16_bf16 v[16:31], v[44:47], v[40:43], v[16:31]
	ds_read2_b64 v[40:43], v89 offset0:28 offset1:30
	s_waitcnt lgkmcnt(0)
	v_mfma_f32_32x32x16_bf16 v[0:15], v[40:43], v[34:37], v[0:15]
	ds_read2_b64 v[38:41], v91 offset0:92 offset1:94
	s_waitcnt lgkmcnt(0)
	v_mfma_f32_32x32x16_bf16 v[16:31], v[38:41], v[34:37], v[16:31]
	s_nop 8
	v_mul_f32_e32 v0, v33, v0
	v_mul_f32_e32 v1, v33, v1
	ds_write2st64_b32 v105, v0, v1 offset1:8
	v_mul_f32_e32 v16, v33, v16
	v_mul_f32_e32 v0, v33, v17
	ds_write2st64_b32 v105, v16, v0 offset0:128 offset1:136
	v_mul_f32_e32 v0, v33, v2
	v_mul_f32_e32 v2, v33, v3
	v_mul_f32_e32 v1, v33, v18
	ds_write2st64_b32 v105, v0, v2 offset0:16 offset1:24
	v_mul_f32_e32 v0, v33, v19
	ds_write2st64_b32 v105, v1, v0 offset0:144 offset1:152
	v_mul_f32_e32 v0, v33, v4
	v_mul_f32_e32 v2, v33, v5
	v_mul_f32_e32 v1, v33, v20
	ds_write2st64_b32 v105, v0, v2 offset0:32 offset1:40
	v_mul_f32_e32 v0, v33, v21
	ds_write2st64_b32 v105, v1, v0 offset0:160 offset1:168
	v_mul_f32_e32 v0, v33, v6
	v_mul_f32_e32 v2, v33, v7
	v_mul_f32_e32 v1, v33, v22
	ds_write2st64_b32 v105, v0, v2 offset0:48 offset1:56
	v_mul_f32_e32 v0, v33, v23
	ds_write2st64_b32 v105, v1, v0 offset0:176 offset1:184
	v_mul_f32_e32 v0, v33, v8
	v_mul_f32_e32 v2, v33, v9
	v_mul_f32_e32 v1, v33, v24
	ds_write2st64_b32 v105, v0, v2 offset0:64 offset1:72
	v_mul_f32_e32 v0, v33, v25
	ds_write2st64_b32 v105, v1, v0 offset0:192 offset1:200
	v_mul_f32_e32 v0, v33, v10
	v_mul_f32_e32 v2, v33, v11
	v_mul_f32_e32 v1, v33, v26
	ds_write2st64_b32 v105, v0, v2 offset0:80 offset1:88
	v_mul_f32_e32 v0, v33, v27
	ds_write2st64_b32 v105, v1, v0 offset0:208 offset1:216
	v_mul_f32_e32 v0, v33, v12
	v_mul_f32_e32 v2, v33, v13
	v_mul_f32_e32 v1, v33, v28
	ds_write2st64_b32 v105, v0, v2 offset0:96 offset1:104
	v_mul_f32_e32 v0, v33, v29
	ds_write2st64_b32 v105, v1, v0 offset0:224 offset1:232
	v_mul_f32_e32 v0, v33, v14
	v_mul_f32_e32 v2, v33, v15
	v_mul_f32_e32 v1, v33, v30
	ds_write2st64_b32 v105, v0, v2 offset0:112 offset1:120
	v_mul_f32_e32 v0, v33, v31
	ds_write2st64_b32 v105, v1, v0 offset0:240 offset1:248
	s_and_saveexec_b64 s[2:3], vcc
	s_cbranch_execz .LBB0_403
	v_cmp_lt_u32_e32 vcc, 15, v100
	s_and_saveexec_b64 s[4:5], vcc
	s_xor_b64 s[4:5], exec, s[4:5]
	v_sub_u32_e32 v1, 30, v108
	v_lshlrev_b32_e64 v0, v100, 1
	v_lshlrev_b32_e64 v1, v1, 1
	v_or3_b32 v0, v0, v1, 1
	s_andn2_saveexec_b64 s[4:5], s[4:5]
	v_sub_u32_e32 v0, 32, v108
	v_lshlrev_b32_e64 v0, v0, -1
	v_not_b32_e32 v0, v0
	s_or_b64 exec, exec, s[4:5]
	v_add_u32_e32 v1, 0x10c00, v32
	ds_write_b32 v1, v0
